# RWKV-7 producer stage B: the eight LDS fragment reads batched ahead of the four MFMAs with counted lgkmcnt waits
# baseline (speedup 1.0000x reference)
.LBB0_184:
	s_andn2_b64 vcc, exec, s[46:47]
	s_cbranch_vccnz .LBB0_186
	ds_read_b128 v[222:225], v102
	ds_read_b128 v[30:33], v93
	ds_read_b128 v[226:229], v102 offset:64
	ds_read_b128 v[34:37], v93 offset:64
	ds_read_b128 v[230:233], v103
	ds_read_b128 v[42:45], v94
	ds_read_b128 v[126:129], v103 offset:64
	ds_read_b128 v[46:49], v94 offset:64
	s_waitcnt lgkmcnt(6)
	v_mfma_f32_16x16x32_bf16 v[38:41], v[222:225], v[30:33], 0
	s_waitcnt lgkmcnt(4)
	v_mfma_f32_16x16x32_bf16 v[38:41], v[226:229], v[34:37], v[38:41]
	s_waitcnt lgkmcnt(2)
	v_mfma_f32_16x16x32_bf16 v[122:125], v[230:233], v[42:45], 0
	s_nop 7
	s_waitcnt vmcnt(5)
	s_nop 0
	v_add_f32_e32 v38, v113, v38
	v_add_f32_e32 v39, v113, v39
	v_mul_f32_e32 v38, 0xbfb8aa3b, v38
	v_mul_f32_e32 v39, 0xbfb8aa3b, v39
	v_exp_f32_e32 v38, v38
	v_exp_f32_e32 v39, v39
	s_waitcnt lgkmcnt(0)
	v_mfma_f32_16x16x32_bf16 v[122:125], v[126:129], v[46:49], v[122:125]
	ds_read2st64_b32 v[126:127], v65 offset0:64 offset1:65
	v_add_f32_e32 v38, 1.0, v38
	v_add_f32_e32 v39, 1.0, v39
	v_rcp_f32_e32 v38, v38
	v_rcp_f32_e32 v39, v39
	s_waitcnt vmcnt(4)
	s_nop 1
	v_add_f32_e32 v122, v114, v122
	v_add_f32_e32 v123, v114, v123
	v_mul_f32_e32 v122, 0xbfb8aa3b, v122
	v_mul_f32_e32 v123, 0xbfb8aa3b, v123
	v_exp_f32_e32 v122, v122
	v_exp_f32_e32 v123, v123
	v_mul_f32_e32 v38, 0xbf1b4598, v38
	v_mul_f32_e32 v39, 0xbf1b4598, v39
	v_mul_f32_e32 v38, 0x3fb8aa3b, v38
	v_mul_f32_e32 v39, 0x3fb8aa3b, v39
	v_add_f32_e32 v122, 1.0, v122
	v_exp_f32_e32 v38, v38
	v_add_f32_e32 v123, 1.0, v123
	v_exp_f32_e32 v39, v39
	v_rcp_f32_e32 v122, v122
	v_rcp_f32_e32 v123, v123
	s_waitcnt vmcnt(3) lgkmcnt(0)
	v_mul_f32_e32 v128, v115, v126
	ds_write2st64_b32 v65, v38, v39 offset0:32 offset1:33
	v_mul_f32_e32 v38, v115, v127
	v_add_f32_e32 v129, -1.0, v122
	ds_write2st64_b32 v65, v128, v38 offset0:96 offset1:97
	v_add_f32_e32 v38, -1.0, v123
	s_waitcnt vmcnt(2)
	v_fma_f32 v129, v116, v129, 1.0
	v_fma_f32 v38, v116, v38, 1.0
	v_mul_f32_e32 v126, v126, v129
	v_mul_f32_e32 v38, v127, v38
	ds_write2st64_b32 v65, v126, v38 offset0:64 offset1:65
	ds_write2st64_b32 v65, v122, v123 offset0:128 offset1:129
	v_add_f32_e32 v38, v114, v124
	v_mul_f32_e32 v38, 0xbfb8aa3b, v38
	v_exp_f32_e32 v38, v38
	v_add_f32_e32 v40, v113, v40
	v_add_f32_e32 v41, v113, v41
	v_mul_f32_e32 v40, 0xbfb8aa3b, v40
	v_add_f32_e32 v38, 1.0, v38
	v_rcp_f32_e32 v122, v38
	v_mul_f32_e32 v41, 0xbfb8aa3b, v41
	ds_read2st64_b32 v[38:39], v65 offset0:66 offset1:67
	v_exp_f32_e32 v40, v40
	v_exp_f32_e32 v41, v41
	v_add_f32_e32 v124, -1.0, v122
	v_fma_f32 v124, v116, v124, 1.0
	v_add_f32_e32 v40, 1.0, v40
	v_add_f32_e32 v41, 1.0, v41
	v_rcp_f32_e32 v40, v40
	s_waitcnt lgkmcnt(0)
	v_mul_f32_e32 v123, v115, v38
	v_mul_f32_e32 v38, v124, v38
	v_add_f32_e32 v124, v114, v125
	v_rcp_f32_e32 v41, v41
	v_mul_f32_e32 v124, 0xbfb8aa3b, v124
	v_exp_f32_e32 v124, v124
	v_mul_f32_e32 v40, 0xbf1b4598, v40
	v_mul_f32_e32 v41, 0xbf1b4598, v41
	v_mul_f32_e32 v40, 0x3fb8aa3b, v40
	v_mul_f32_e32 v41, 0x3fb8aa3b, v41
	v_exp_f32_e32 v40, v40
	v_add_f32_e32 v124, 1.0, v124
	v_exp_f32_e32 v41, v41
	v_rcp_f32_e32 v124, v124
	ds_write2st64_b32 v65, v40, v41 offset0:34 offset1:35
	v_mul_f32_e32 v40, v115, v39
	ds_write2st64_b32 v65, v123, v40 offset0:98 offset1:99
	v_add_f32_e32 v40, -1.0, v124
	v_fma_f32 v40, v116, v40, 1.0
	v_mul_f32_e32 v39, v40, v39
	ds_write2st64_b32 v65, v38, v39 offset0:66 offset1:67
	ds_write2st64_b32 v65, v122, v124 offset0:130 offset1:131
	ds_read_b128 v[38:41], v105
	s_waitcnt lgkmcnt(0)
	v_mfma_f32_16x16x32_bf16 v[30:33], v[38:41], v[30:33], 0
	ds_read_b128 v[38:41], v106 offset:64
	s_waitcnt lgkmcnt(0)
	v_mfma_f32_16x16x32_bf16 v[30:33], v[38:41], v[34:37], v[30:33]
	ds_read_b128 v[34:37], v107
	ds_read_b128 v[38:41], v108 offset:64
	s_nop 5
	v_add_f32_e32 v30, v113, v30
	s_waitcnt lgkmcnt(1)
	v_mfma_f32_16x16x32_bf16 v[34:37], v[34:37], v[42:45], 0
	v_add_f32_e32 v31, v113, v31
	v_mul_f32_e32 v30, 0xbfb8aa3b, v30
	v_mul_f32_e32 v31, 0xbfb8aa3b, v31
	v_exp_f32_e32 v30, v30
	v_exp_f32_e32 v31, v31
	s_waitcnt lgkmcnt(0)
	v_mfma_f32_16x16x32_bf16 v[34:37], v[38:41], v[46:49], v[34:37]
	ds_read2st64_b32 v[38:39], v65 offset0:80 offset1:81
	v_add_f32_e32 v30, 1.0, v30
	v_add_f32_e32 v31, 1.0, v31
	v_rcp_f32_e32 v30, v30
	v_rcp_f32_e32 v31, v31
	s_nop 2
	v_add_f32_e32 v34, v114, v34
	v_add_f32_e32 v35, v114, v35
	v_mul_f32_e32 v34, 0xbfb8aa3b, v34
	v_mul_f32_e32 v35, 0xbfb8aa3b, v35
	v_exp_f32_e32 v34, v34
	v_exp_f32_e32 v35, v35
	v_mul_f32_e32 v30, 0xbf1b4598, v30
	v_mul_f32_e32 v31, 0xbf1b4598, v31
	v_mul_f32_e32 v30, 0x3fb8aa3b, v30
	v_mul_f32_e32 v31, 0x3fb8aa3b, v31
	v_add_f32_e32 v34, 1.0, v34
	v_exp_f32_e32 v30, v30
	v_add_f32_e32 v35, 1.0, v35
	v_exp_f32_e32 v31, v31
	v_rcp_f32_e32 v34, v34
	v_rcp_f32_e32 v35, v35
	s_waitcnt lgkmcnt(0)
	v_mul_f32_e32 v40, v115, v38
	ds_write2st64_b32 v65, v30, v31 offset0:48 offset1:49
	v_mul_f32_e32 v30, v115, v39
	v_add_f32_e32 v41, -1.0, v34
	ds_write2st64_b32 v65, v40, v30 offset0:112 offset1:113
	v_add_f32_e32 v30, -1.0, v35
	v_fma_f32 v41, v116, v41, 1.0
	v_fma_f32 v30, v116, v30, 1.0
	v_mul_f32_e32 v38, v38, v41
	v_mul_f32_e32 v30, v39, v30
	ds_write2st64_b32 v65, v38, v30 offset0:80 offset1:81
	ds_write2st64_b32 v65, v34, v35 offset0:144 offset1:145
	v_add_f32_e32 v30, v114, v36
	v_mul_f32_e32 v30, 0xbfb8aa3b, v30
	v_exp_f32_e32 v30, v30
	v_add_f32_e32 v34, v113, v32
	v_add_f32_e32 v33, v113, v33
	v_mul_f32_e32 v34, 0xbfb8aa3b, v34
	v_add_f32_e32 v30, 1.0, v30
	v_rcp_f32_e32 v32, v30
	v_mul_f32_e32 v33, 0xbfb8aa3b, v33
	ds_read2st64_b32 v[30:31], v65 offset0:82 offset1:83
	v_exp_f32_e32 v34, v34
	v_exp_f32_e32 v33, v33
	v_add_f32_e32 v36, -1.0, v32
	v_fma_f32 v36, v116, v36, 1.0
	v_add_f32_e32 v34, 1.0, v34
	v_add_f32_e32 v33, 1.0, v33
	v_rcp_f32_e32 v34, v34
	s_waitcnt lgkmcnt(0)
	v_mul_f32_e32 v35, v115, v30
	v_mul_f32_e32 v30, v36, v30
	v_add_f32_e32 v36, v114, v37
	v_rcp_f32_e32 v33, v33
	v_mul_f32_e32 v36, 0xbfb8aa3b, v36
	v_exp_f32_e32 v36, v36
	v_mul_f32_e32 v34, 0xbf1b4598, v34
	v_mul_f32_e32 v33, 0xbf1b4598, v33
	v_mul_f32_e32 v34, 0x3fb8aa3b, v34
	v_mul_f32_e32 v33, 0x3fb8aa3b, v33
	v_exp_f32_e32 v34, v34
	v_add_f32_e32 v36, 1.0, v36
	v_exp_f32_e32 v33, v33
	v_rcp_f32_e32 v36, v36
	ds_write2st64_b32 v65, v34, v33 offset0:50 offset1:51
	v_mul_f32_e32 v33, v115, v31
	ds_write2st64_b32 v65, v35, v33 offset0:114 offset1:115
	v_add_f32_e32 v33, -1.0, v36
	v_fma_f32 v33, v116, v33, 1.0
	v_mul_f32_e32 v31, v33, v31
	ds_write2st64_b32 v65, v30, v31 offset0:82 offset1:83
	ds_write2st64_b32 v65, v32, v36 offset0:146 offset1:147
